# S5 pass C: next-block D*u inputs prefetched at the top of the block and consumed at the next top (no in-block wait)
# speedup vs baseline: 1.0027x; 1.0027x over previous
; __device__ __forceinline__ unsigned pk2(float lo, float hi) { f32x2 v; v.x = lo; v.y = hi; return __builtin_bit_cast(unsigned, __builtin_convertvector(v, hwbf2)); }
; __device__ __forceinline__ void s5_lambda(const Args& a, int g, int p, float& lbr, float& lbi, float& qr, float& qi) {
;     const float lr = a.in[I_LRE][g * 64 + p], li = a.in[I_LIM][g * 64 + p], dt = expf(a.in[I_LDT][g]);
;     const float mag = expf(lr * dt), ang = li * dt;
;     lbr = mag * cosf(ang); lbi = mag * sinf(ang);
;     const float den = lr * lr + li * li;
;     qr = ((lbr - 1.f) * lr + lbi * li) / den; qi = (lbi * lr - (lbr - 1.f) * li) / den;
; }
; __device__ __forceinline__ void s5_consts(const Args& a, int g, int lane, S5Consts& c) {
;     const int r = lane & 31, hf = lane >> 5;
;     float lb0r, lb0i, q0r, q0i, lb1r, lb1i, q1r, q1i;
;     s5_lambda(a, g, r, lb0r, lb0i, q0r, q0i); s5_lambda(a, g, 32 + r, lb1r, lb1i, q1r, q1i);
;     c.lbr = hf ? lb1r : lb0r; c.lbi = hf ? lb1i : lb0i;
; #pragma unroll
;     for (int nb = 0; nb < 4; ++nb) {
;         const int ps = r + 32 * (nb >> 1); const float qr = (nb >> 1) ? q1r : q0r, qi = (nb >> 1) ? q1i : q0i;
;         const float* br = a.in[I_BRE] + (size_t)(g * 64 + ps) * 16 + 8 * hf; const float* bi = a.in[I_BIM] + (size_t)(g * 64 + ps) * 16 + 8 * hf;
;         float v[8];
; #pragma unroll
;         for (int j = 0; j < 8; ++j) v[j] = (nb & 1) ? (qr * bi[j] + qi * br[j]) : (qr * br[j] - qi * bi[j]);
;         u32x4 w; w.x = pk2(v[0], v[1]); w.y = pk2(v[2], v[3]); w.z = pk2(v[4], v[5]); w.w = pk2(v[6], v[7]);
;         c.bb[nb] = __builtin_bit_cast(bf16x8, w);
;     }
; }
.LBB0_891:
	s_or_b64 exec, exec, s[2:3]
	s_waitcnt vmcnt(0)
	v_mul_f32_e32 v19, v4, v10
	v_mul_f32_e32 v20, 0x3fb8aa3b, v19
	v_fma_f32 v21, v19, s26, -v20
	v_rndne_f32_e32 v22, v20
	v_fmac_f32_e32 v21, 0x32a5705f, v19
	v_sub_f32_e32 v20, v20, v22
	v_add_f32_e32 v20, v20, v21
	v_exp_f32_e32 v20, v20
	v_cvt_i32_f32_e32 v21, v22
	s_lshl_b32 s2, s12, 5
	s_lshl_b32 s3, s12, 10
	v_cmp_ngt_f32_e32 vcc, s27, v19
	v_ldexp_f32 v20, v20, v21
	s_and_b32 s2, s2, 0xffffe000
	s_and_b32 s3, s3, 0x1c00
	v_cndmask_b32_e32 v20, 0, v20, vcc
	v_cmp_nlt_f32_e32 vcc, s28, v19
	s_or_b32 s7, s2, s3
	s_and_b32 s2, s19, 0xffffe000
	v_cndmask_b32_e32 v24, v164, v20, vcc
	v_mul_f32_e32 v20, v16, v16
	v_or_b32_e32 v22, s2, v121
	s_and_b32 s2, s24, 0x1c00
	v_fmamk_f32 v21, v20, 0x37d75334, v161
	v_or_b32_e32 v130, s2, v22
	v_fmaak_f32 v21, v20, v21, 0x3d2aabf7
	v_fmamk_f32 v22, v20, 0xb94c1982, v162
	v_fmaak_f32 v21, v20, v21, 0xbf000004
	v_fmaak_f32 v22, v20, v22, 0xbe2aaa9d
	v_fma_f32 v21, v20, v21, 1.0
	v_mul_f32_e32 v20, v20, v22
	v_mul_f32_e32 v4, v8, v4
	v_fmac_f32_e32 v16, v16, v20
	v_mul_f32_e32 v20, 0x3fb8aa3b, v4
	v_fma_f32 v22, v4, s26, -v20
	v_rndne_f32_e32 v23, v20
	v_fmac_f32_e32 v22, 0x32a5705f, v4
	v_sub_f32_e32 v20, v20, v23
	v_add_f32_e32 v20, v20, v22
	v_exp_f32_e32 v20, v20
	v_cvt_i32_f32_e32 v22, v23
	v_lshlrev_b32_e32 v19, 30, v17
	v_and_b32_e32 v17, 1, v17
	v_cmp_eq_u32_e32 vcc, 0, v17
	v_xor_b32_e32 v3, v3, v2
	v_mov_b32_e32 v17, v8
	v_cndmask_b32_e64 v16, -v16, v21, vcc
	v_bitop3_b32 v19, v19, v16, s54 bitop3:0x6c
	v_ldexp_f32 v16, v20, v22
	v_cmp_ngt_f32_e32 vcc, s27, v4
	v_mov_b32_e32 v21, v0
	v_lshlrev_b32_e32 v112, 6, v1
	v_cndmask_b32_e32 v16, 0, v16, vcc
	v_cmp_nlt_f32_e32 vcc, s28, v4
	v_lshlrev_b32_e32 v4, 30, v9
	v_and_b32_e32 v4, 0x80000000, v4
	v_xor_b32_e32 v3, v3, v4
	v_and_b32_e32 v4, 1, v9
	v_mul_f32_e32 v9, v7, v7
	v_cndmask_b32_e32 v22, v164, v16, vcc
	v_fmamk_f32 v16, v9, 0xb94c1982, v162
	v_fmaak_f32 v16, v9, v16, 0xbe2aaa9d
	v_mul_f32_e32 v16, v9, v16
	v_fmac_f32_e32 v7, v7, v16
	v_fmamk_f32 v16, v9, 0x37d75334, v161
	v_fmaak_f32 v16, v9, v16, 0x3d2aabf7
	v_fmaak_f32 v16, v9, v16, 0xbf000004
	v_fma_f32 v9, v9, v16, 1.0
	v_cmp_eq_u32_e32 vcc, 0, v4
	v_readlane_b32 s56, v254, 43
	v_readlane_b32 s64, v254, 51
	v_cndmask_b32_e32 v4, v9, v7, vcc
	v_xor_b32_e32 v3, v3, v4
	v_cmp_class_f32_e64 vcc, v2, s53
	v_mul_f32_e32 v4, v5, v5
	v_fmamk_f32 v7, v4, 0xb94c1982, v162
	v_cndmask_b32_e32 v2, v168, v3, vcc
	v_mul_f32_e32 v16, v22, v2
	v_lshlrev_b32_e32 v2, 30, v6
	v_and_b32_e32 v3, 1, v6
	v_fmamk_f32 v6, v4, 0x37d75334, v161
	v_fmaak_f32 v6, v4, v6, 0x3d2aabf7
	v_fmaak_f32 v6, v4, v6, 0xbf000004
	v_fmaak_f32 v7, v4, v7, 0xbe2aaa9d
	v_fma_f32 v6, v4, v6, 1.0
	v_mul_f32_e32 v4, v4, v7
	v_fmac_f32_e32 v5, v5, v4
	v_cmp_eq_u32_e64 s[2:3], 0, v3
	v_readlane_b32 s65, v254, 52
	v_readlane_b32 s66, v254, 53
	v_cndmask_b32_e64 v3, -v5, v6, s[2:3]
	v_bitop3_b32 v2, v2, v3, s54 bitop3:0x6c
	v_cndmask_b32_e32 v6, v168, v2, vcc
	v_fma_f32 v20, v22, v6, -1.0
	v_pk_mul_f32 v[2:3], v[8:9], v[16:17] op_sel_hi:[0,1]
	v_pk_mul_f32 v[4:5], v[0:1], v[20:21] op_sel_hi:[0,1]
	v_sub_f32_e32 v17, v2, v4
	v_add_f32_e32 v25, v3, v5
	v_div_scale_f32 v2, s[2:3], v25, v25, v17
	v_rcp_f32_e32 v34, v2
	v_cmp_class_f32_e64 s[2:3], v13, s53
	v_mul_f32_e32 v37, v22, v6
	v_mov_b32_e32 v9, v0
	v_fma_f32 v3, -v2, v34, 1.0
	v_fmac_f32_e32 v34, v3, v34
	v_div_scale_f32 v3, vcc, v17, v25, v17
	v_cndmask_b32_e64 v35, v168, v19, s[2:3]
	v_mul_f32_e32 v19, v3, v34
	v_fma_f32 v4, -v2, v19, v3
	v_fmac_f32_e32 v19, v4, v34
	v_lshl_add_u64 v[4:5], v[118:119], 0, v[112:113]
	v_fma_f32 v38, -v2, v19, v3
	v_lshl_add_u64 v[22:23], v[116:117], 0, v[112:113]
	global_load_dwordx4 v[0:3], v[4:5], off offset:16
	global_load_dwordx4 v[26:29], v[4:5], off
	s_nop 0
	global_load_dwordx4 v[4:7], v[22:23], off offset:16
	global_load_dwordx4 v[30:33], v[22:23], off
	v_mov_b32_e32 v21, v16
	v_pk_mul_f32 v[8:9], v[8:9], v[20:21]
	v_xor_b32_e32 v13, v14, v13
	v_add_f32_e32 v21, v8, v9
	v_div_scale_f32 v8, s[4:5], v25, v25, v21
	v_rcp_f32_e32 v22, v8
	v_div_fmas_f32 v9, v38, v34, v19
	v_div_fixup_f32 v20, v9, v25, v17
	v_mov_b32_e32 v14, v11
	v_fma_f32 v9, -v8, v22, 1.0
	v_fmac_f32_e32 v22, v9, v22
	v_div_scale_f32 v9, vcc, v21, v25, v21
	v_mul_f32_e32 v17, v9, v22
	v_fma_f32 v19, -v8, v17, v9
	v_fmac_f32_e32 v17, v19, v22
	v_fma_f32 v23, -v8, v17, v9
	v_mul_f32_e32 v8, v18, v18
	v_fmamk_f32 v9, v8, 0xb94c1982, v162
	v_fmaak_f32 v9, v8, v9, 0xbe2aaa9d
	v_mul_f32_e32 v9, v8, v9
	v_fmac_f32_e32 v18, v18, v9
	v_fmamk_f32 v9, v8, 0x37d75334, v161
	v_fmaak_f32 v9, v8, v9, 0x3d2aabf7
	v_fmaak_f32 v9, v8, v9, 0xbf000004
	v_fma_f32 v8, v8, v9, 1.0
	v_and_b32_e32 v9, 1, v15
	v_cmp_eq_u32_e64 s[4:5], 0, v9
	v_lshlrev_b32_e32 v9, 30, v15
	v_and_b32_e32 v9, 0x80000000, v9
	v_cndmask_b32_e64 v8, v8, v18, s[4:5]
	v_xor_b32_e32 v9, v13, v9
	v_xor_b32_e32 v8, v9, v8
	v_cndmask_b32_e64 v8, v168, v8, s[2:3]
	v_mul_f32_e32 v19, v24, v8
	v_fma_f32 v18, v24, v35, -1.0
	v_pk_mul_f32 v[8:9], v[10:11], v[18:19]
	v_mul_f32_e32 v36, v24, v35
	v_add_f32_e32 v13, v8, v9
	v_mov_b32_e32 v8, v19
	v_mov_b32_e32 v9, v10
	v_pk_mul_f32 v[8:9], v[10:11], v[8:9] op_sel_hi:[0,1]
	v_mov_b32_e32 v10, v18
	v_pk_mul_f32 v[10:11], v[14:15], v[10:11] op_sel_hi:[0,1]
	v_add_f32_e32 v9, v9, v11
	v_div_scale_f32 v11, s[2:3], v9, v9, v13
	v_rcp_f32_e32 v14, v11
	v_div_fmas_f32 v15, v23, v22, v17
	v_div_fixup_f32 v24, v15, v25, v21
	v_sub_f32_e32 v8, v8, v10
	v_fma_f32 v15, -v11, v14, 1.0
	v_fmac_f32_e32 v14, v15, v14
	v_div_scale_f32 v15, vcc, v13, v9, v13
	v_mul_f32_e32 v17, v15, v14
	v_fma_f32 v18, -v11, v17, v15
	v_fmac_f32_e32 v17, v18, v14
	v_div_scale_f32 v10, s[2:3], v9, v9, v8
	v_fma_f32 v11, -v11, v17, v15
	v_rcp_f32_e32 v15, v10
	v_div_fmas_f32 v11, v11, v14, v17
	v_div_fixup_f32 v18, v11, v9, v13
	v_lshl_or_b32 v112, v12, 6, v169
	v_fma_f32 v11, -v10, v15, 1.0
	v_fmac_f32_e32 v15, v11, v15
	v_div_scale_f32 v11, vcc, v8, v9, v8
	v_mul_f32_e32 v13, v11, v15
	v_fma_f32 v14, -v10, v13, v11
	v_fmac_f32_e32 v13, v14, v15
	v_fma_f32 v10, -v10, v13, v11
	v_div_fmas_f32 v10, v10, v15, v13
	v_div_fixup_f32 v22, v10, v9, v8
	v_lshlrev_b32_e32 v17, 2, v123
	s_waitcnt vmcnt(2)
; __device__ __forceinline__ void s5_consts(const Args& a, int g, int lane, S5Consts& c) {
;     ...
;     for (int nb = 0; nb < 4; ++nb) {
;         const int ps = r + 32 * (nb >> 1); const float qr = (nb >> 1) ? q1r : q0r, qi = (nb >> 1) ? q1i : q0i;
;         const float* br = a.in[I_BRE] + (size_t)(g * 64 + ps) * 16 + 8 * hf; const float* bi = a.in[I_BIM] + (size_t)(g * 64 + ps) * 16 + 8 * hf;
;         float v[8];
; #pragma unroll
;         for (int j = 0; j < 8; ++j) v[j] = (nb & 1) ? (qr * bi[j] + qi * br[j]) : (qr * br[j] - qi * bi[j]);
;         u32x4 w; w.x = pk2(v[0], v[1]); w.y = pk2(v[2], v[3]); w.z = pk2(v[4], v[5]); w.w = pk2(v[6], v[7]);
;         c.bb[nb] = __builtin_bit_cast(bf16x8, w);
;     }
; }
; __device__ __forceinline__ void s5_passC_run(const Args& a, LAS unsigned char* wlds, int row0, int nblk, int g, int lane, float& hr, float& hi) {
;     S5Consts c; s5_consts(a, g, lane, c);
;     const int r16 = lane & 15, q4 = lane >> 4;
;     bf16x8 ca[4];
; #pragma unroll
;     for (int kb = 0; kb < 4; ++kb) { float v[8];
; #pragma unroll
;         for (int j = 0; j < 8; ++j) { const int comp = 32 * kb + 8 * q4 + j, p = comp >> 1; v[j] = (comp & 1) ? -a.in[I_CIM][(size_t)(g * 16 + r16) * 64 + p] : a.in[I_CRE][(size_t)(g * 16 + r16) * 64 + p]; }
;         u32x4 w; w.x = pk2(v[0], v[1]); w.y = pk2(v[2], v[3]); w.z = pk2(v[4], v[5]); w.w = pk2(v[6], v[7]); ca[kb] = __builtin_bit_cast(bf16x8, w); }
;     bf16x4 ga[2];
; #pragma unroll
;     for (int mb = 0; mb < 2; ++mb) { float v[4];
; #pragma unroll
;         for (int j = 0; j < 4; ++j) v[j] = a.in[I_GLUW][(size_t)(g * 16 + 4 * q4 + j) * 32 + mb * 16 + r16];
;         u32x2 w; w.x = pk2(v[0], v[1]); w.y = pk2(v[2], v[3]); ga[mb] = __builtin_bit_cast(bf16x4, w); }
;     f32x4 dD, gb0, gb1;
; #pragma unroll
;     for (int j = 0; j < 4; ++j) { dD[j] = a.in[I_S5D][g * 16 + 4 * q4 + j]; gb0[j] = a.in[I_GLUB][g * 32 + 4 * q4 + j]; gb1[j] = a.in[I_GLUB][g * 32 + 16 + 4 * q4 + j]; }
;     const bf16_t* proj = (const bf16_t*)(a.ws + WS_PROJ);
;     bf16_t* mixin = (bf16_t*)(a.ws + WS_MIXIN);
;     const bf16_t* up_ = proj + (size_t)(row0 + (lane & 31)) * NPROJ + 1536 + g * 16 + 8 * (lane >> 5);
;     bf16x8 uf = *(const bf16x8*)up_;
;     u32x2 uus[2], uun[2];
; #pragma unroll
;     for (int sb = 0; sb < 2; ++sb) uus[sb] = *(const u32x2*)(proj + (size_t)(row0 + sb * 16 + r16) * NPROJ + 1536 + g * 16 + 4 * q4);
	v_pk_mul_f32 v[8:9], v[20:21], v[26:27] op_sel_hi:[0,1]
	v_pk_mul_f32 v[26:27], v[24:25], v[26:27] op_sel_hi:[0,1]
	s_waitcnt vmcnt(0)
	v_pk_fma_f32 v[42:43], v[24:25], v[30:31], v[8:9] op_sel_hi:[0,1,1] neg_lo:[0,0,1] neg_hi:[0,0,1]
	v_pk_fma_f32 v[30:31], v[20:21], v[30:31], v[26:27] op_sel_hi:[0,1,1]
	v_pk_mul_f32 v[26:27], v[20:21], v[28:29] op_sel_hi:[0,1]
	v_pk_fma_f32 v[26:27], v[24:25], v[32:33], v[26:27] op_sel_hi:[0,1,1] neg_lo:[0,0,1] neg_hi:[0,0,1]
	v_lshl_add_u64 v[38:39], v[116:117], 0, v[112:113]
	v_lshl_add_u64 v[12:13], v[118:119], 0, v[112:113]
	v_cvt_pk_bf16_f32 v65, v26, v27
	v_pk_mul_f32 v[26:27], v[24:25], v[28:29] op_sel_hi:[0,1]
	v_lshl_or_b32 v17, s8, 12, v17
	v_readlane_b32 s67, v254, 54
	v_readlane_b32 s68, v254, 55
	v_readlane_b32 s69, v254, 56
	v_readlane_b32 s70, v254, 57
	v_readlane_b32 s71, v254, 58
	s_mov_b64 s[44:45], s[64:65]
	s_lshl_b32 s2, s8, 4
	v_cndmask_b32_e64 v132, v36, v37, s[0:1]
	global_load_dwordx4 v[8:11], v[12:13], off offset:16
	global_load_dwordx4 v[34:37], v[12:13], off
	s_nop 0
	global_load_dwordx4 v[12:15], v[38:39], off offset:16
	s_nop 0
	global_load_dwordx4 v[38:41], v[38:39], off
	v_cvt_pk_bf16_f32 v64, v42, v43
	v_pk_fma_f32 v[46:47], v[20:21], v[32:33], v[26:27] op_sel_hi:[0,1,1]
	s_mov_b64 s[46:47], s[66:67]
	global_load_dwordx4 v[26:29], v17, s[44:45]
	global_load_dwordx4 v[42:45], v17, s[46:47]
	global_load_dwordx4 v[50:53], v17, s[44:45] offset:64
	global_load_dwordx4 v[54:57], v17, s[46:47] offset:64
	global_load_dwordx4 v[58:61], v17, s[44:45] offset:128
	global_load_dwordx4 v[104:107], v17, s[46:47] offset:128
	global_load_dwordx4 v[108:111], v17, s[44:45] offset:192
	global_load_dwordx4 v[138:141], v17, s[46:47] offset:192
	v_or_b32_e32 v17, s2, v120
	v_lshlrev_b32_e32 v21, 5, v17
	v_or_b32_e32 v23, v21, v121
	v_readlane_b32 s57, v254, 44
	v_readlane_b32 s58, v254, 45
	v_readlane_b32 s59, v254, 46
	v_readlane_b32 s60, v254, 47
	v_readlane_b32 s61, v254, 48
	v_readlane_b32 s62, v254, 49
	v_readlane_b32 s63, v254, 50
	v_lshlrev_b32_e32 v23, 2, v23
	v_or_b32_e32 v21, v21, v158
	s_lshl_b32 s8, s8, 5
	s_mov_b64 s[48:49], s[68:69]
	s_mov_b64 s[50:51], s[70:71]
	v_or_b32_e32 v25, 0x100, v23
	v_lshlrev_b32_e32 v21, 2, v21
	v_or_b32_e32 v32, s8, v120
	v_readlane_b32 s56, v254, 23
	global_load_dword v131, v23, s[50:51]
	global_load_dword v133, v23, s[50:51] offset:128
	global_load_dword v142, v25, s[50:51]
	global_load_dword v143, v21, s[50:51] offset:128
	s_nop 0
	global_load_dword v21, v21, s[50:51] offset:384
	s_nop 0
	global_load_dword v25, v25, s[50:51] offset:64
	s_nop 0
	global_load_dword v144, v23, s[50:51] offset:384
	s_nop 0
	global_load_dword v23, v23, s[50:51] offset:64
	v_lshlrev_b32_e32 v17, 2, v17
	v_lshlrev_b32_e32 v32, 2, v32
	v_readlane_b32 s57, v254, 24
	global_load_dwordx4 v[68:71], v17, s[48:49]
	s_nop 3
	global_load_dwordx4 v[72:75], v32, s[56:57]
	global_load_dwordx4 v[76:79], v32, s[56:57] offset:64
	v_or_b32_e32 v32, s7, v115
	v_ashrrev_i32_e32 v33, 31, v32
	v_lshlrev_b64 v[32:33], 12, v[32:33]
	v_or_b32_e32 v136, s7, v121
	v_lshl_add_u64 v[32:33], s[10:11], 0, v[32:33]
	v_or_b32_e32 v48, 16, v136
	v_lshl_add_u64 v[32:33], v[32:33], 0, s[8:9]
	v_lshlrev_b32_e32 v112, 1, v114
	v_ashrrev_i32_e32 v137, 31, v136
	v_ashrrev_i32_e32 v49, 31, v48
	v_lshl_add_u64 v[134:135], v[32:33], 0, v[112:113]
	v_lshlrev_b64 v[32:33], 12, v[136:137]
	v_lshlrev_b64 v[48:49], 12, v[48:49]
	v_lshl_add_u64 v[32:33], s[10:11], 0, v[32:33]
	v_lshl_add_u64 v[48:49], s[10:11], 0, v[48:49]
	v_lshl_add_u64 v[32:33], v[32:33], 0, s[8:9]
	v_lshlrev_b32_e32 v112, 1, v120
	v_lshl_add_u64 v[48:49], v[48:49], 0, s[8:9]
	v_lshl_add_u64 v[32:33], v[32:33], 0, v[112:113]
	v_lshl_add_u64 v[48:49], v[48:49], 0, v[112:113]
	global_load_dwordx4 v[88:91], v[134:135], off offset:3072
	s_nop 0
	global_load_dwordx2 v[32:33], v[32:33], off offset:3072
	s_nop 0
	global_load_dwordx2 v[48:49], v[48:49], off offset:3072
	s_mov_b32 s6, 0
	v_cvt_pk_bf16_f32 v80, v30, v31
	v_cvt_pk_bf16_f32 v81, v46, v47
	s_lshl_b32 s2, s2, 1
	v_readlane_b32 s58, v254, 25
	v_readlane_b32 s59, v254, 26
	v_readlane_b32 s60, v254, 27
	v_readlane_b32 s61, v254, 28
	v_readlane_b32 s62, v254, 29
	v_readlane_b32 s63, v254, 30
	v_readlane_b32 s64, v254, 31
	v_readlane_b32 s65, v254, 32
	v_readlane_b32 s66, v254, 33
	v_readlane_b32 s67, v254, 34
	v_readlane_b32 s68, v254, 35
	v_readlane_b32 s69, v254, 36
	v_readlane_b32 s70, v254, 37
	v_readlane_b32 s71, v254, 38
	s_waitcnt vmcnt(9)
	v_pk_mul_f32 v[62:63], v[20:21], v[0:1] op_sel_hi:[0,1]
	s_waitcnt vmcnt(8)
	v_pk_mul_f32 v[0:1], v[24:25], v[0:1] op_sel_hi:[0,1]
	v_pk_fma_f32 v[62:63], v[24:25], v[4:5], v[62:63] op_sel_hi:[0,1,1] neg_lo:[0,0,1] neg_hi:[0,0,1]
	v_pk_fma_f32 v[0:1], v[20:21], v[4:5], v[0:1] op_sel_hi:[0,1,1]
	v_pk_mul_f32 v[4:5], v[20:21], v[2:3] op_sel_hi:[0,1]
	v_pk_mul_f32 v[2:3], v[24:25], v[2:3] op_sel_hi:[0,1]
	v_pk_fma_f32 v[2:3], v[20:21], v[6:7], v[2:3] op_sel_hi:[0,1,1]
	v_cvt_pk_bf16_f32 v82, v0, v1
	v_cvt_pk_bf16_f32 v83, v2, v3
	s_waitcnt vmcnt(6)
; #define LAS __attribute__((address_space(3)))
; __device__ __forceinline__ unsigned pk2(float lo, float hi) { f32x2 v; v.x = lo; v.y = hi; return __builtin_bit_cast(unsigned, __builtin_convertvector(v, hwbf2)); }
; #define MFMA32(a, b, c) __builtin_amdgcn_mfma_f32_32x32x16_bf16((a), (b), (c), 0, 0, 0)
; template <bool STORE>
; __device__ __forceinline__ void s5_block(const Args& a, const S5Consts& c, const bf16x8 uf, int lane, float& hr, float& hi, LAS unsigned char* wl, const bf16_t* nxt, bf16x8& nuf) {
;     f32x16 bu[4];
; #pragma unroll
;     for (int nb = 0; nb < 4; ++nb) bu[nb] = MFMA32(uf, c.bb[nb], zero16());
;     asm volatile("" ::: "memory");
;     nuf = *(const bf16x8*)nxt;
;     asm volatile("" ::: "memory");
; #pragma unroll
;     for (int i = 0; i < 16; ++i) {
;         auto s0 = __builtin_amdgcn_permlane32_swap(__float_as_uint(bu[0][i]), __float_as_uint(bu[2][i]), false, false);
;         auto s1 = __builtin_amdgcn_permlane32_swap(__float_as_uint(bu[1][i]), __float_as_uint(bu[3][i]), false, false);
;         bu[0][i] = __uint_as_float(s0[0]); bu[2][i] = __uint_as_float(s0[1]); bu[1][i] = __uint_as_float(s1[0]); bu[3][i] = __uint_as_float(s1[1]);
;     }
;     const float nlbi = -c.lbi;
; #pragma unroll
;     for (int ib = 0; ib < 4; ++ib) {
; #pragma unroll
;         for (int j = 0; j < 4; ++j) { const float nr = __builtin_fmaf(c.lbr, hr, __builtin_fmaf(nlbi, hi, bu[0][4 * ib + j])), ni = __builtin_fmaf(c.lbr, hi, __builtin_fmaf(c.lbi, hr, bu[1][4 * ib + j])); hr = nr; hi = ni; if (STORE) *(LAS unsigned*)(wl + (8 * ib + j) * 272 + lane * 4) = pk2(hr, hi); }
; __device__ __forceinline__ void s5_passC_run(const Args& a, LAS unsigned char* wlds, int row0, int nblk, int g, int lane, float& hr, float& hi) {
;     ...
;     bf16x8 uf = *(const bf16x8*)up_;
;     u32x2 uus[2], uun[2];
; #pragma unroll
;     for (int sb = 0; sb < 2; ++sb) uus[sb] = *(const u32x2*)(proj + (size_t)(row0 + sb * 16 + r16) * NPROJ + 1536 + g * 16 + 4 * q4);
;     for (int blk = 0; blk < nblk; ++blk) {
;         const int rb = row0 + blk * 32;
;         const int nb = blk < nblk - 1 ? blk + 1 : blk; bf16x8 nuf;
;         s5_block<true>(a, c, uf, lane, hr, hi, wlds, up_ + (size_t)nb * 32 * NPROJ, nuf); uf = nuf;
; #pragma unroll
;         for (int sb = 0; sb < 2; ++sb) uun[sb] = *(const u32x2*)(proj + (size_t)(row0 + nb * 32 + sb * 16 + r16) * NPROJ + 1536 + g * 16 + 4 * q4);
	v_pk_mul_f32 v[0:1], v[22:23], v[34:35] op_sel_hi:[0,1]
	v_pk_mul_f32 v[2:3], v[22:23], v[36:37] op_sel_hi:[0,1]
	v_pk_fma_f32 v[0:1], v[18:19], v[38:39], v[0:1] op_sel_hi:[0,1,1] neg_lo:[0,0,1] neg_hi:[0,0,1]
	v_pk_fma_f32 v[2:3], v[18:19], v[40:41], v[2:3] op_sel_hi:[0,1,1] neg_lo:[0,0,1] neg_hi:[0,0,1]
	v_cvt_pk_bf16_f32 v84, v0, v1
	v_pk_mul_f32 v[0:1], v[18:19], v[34:35] op_sel_hi:[0,1]
	v_cvt_pk_bf16_f32 v85, v2, v3
	v_pk_mul_f32 v[2:3], v[18:19], v[36:37] op_sel_hi:[0,1]
	v_pk_fma_f32 v[4:5], v[24:25], v[6:7], v[4:5] op_sel_hi:[0,1,1] neg_lo:[0,0,1] neg_hi:[0,0,1]
	v_pk_fma_f32 v[0:1], v[22:23], v[38:39], v[0:1] op_sel_hi:[0,1,1]
	v_pk_fma_f32 v[2:3], v[22:23], v[40:41], v[2:3] op_sel_hi:[0,1,1]
	v_cvt_pk_bf16_f32 v67, v4, v5
	v_pk_mul_f32 v[4:5], v[22:23], v[8:9] op_sel_hi:[0,1]
	v_pk_mul_f32 v[6:7], v[22:23], v[10:11] op_sel_hi:[0,1]
	v_cvt_pk_bf16_f32 v92, v0, v1
	v_cvt_pk_bf16_f32 v93, v2, v3
	v_xor_b32_e32 v0, 0x80000000, v42
	v_xor_b32_e32 v1, 0x80000000, v43
	v_xor_b32_e32 v2, 0x80000000, v44
	v_xor_b32_e32 v3, 0x80000000, v45
	v_pk_fma_f32 v[4:5], v[18:19], v[12:13], v[4:5] op_sel_hi:[0,1,1] neg_lo:[0,0,1] neg_hi:[0,0,1]
	v_pk_fma_f32 v[6:7], v[18:19], v[14:15], v[6:7] op_sel_hi:[0,1,1] neg_lo:[0,0,1] neg_hi:[0,0,1]
	v_cvt_pk_bf16_f32 v96, v26, v0
	v_cvt_pk_bf16_f32 v97, v27, v1
	v_cvt_pk_bf16_f32 v98, v28, v2
	v_cvt_pk_bf16_f32 v99, v29, v3
	v_xor_b32_e32 v0, 0x80000000, v54
	v_xor_b32_e32 v1, 0x80000000, v55
	v_xor_b32_e32 v2, 0x80000000, v56
	v_xor_b32_e32 v3, 0x80000000, v57
	v_cvt_pk_bf16_f32 v86, v4, v5
	v_pk_mul_f32 v[4:5], v[18:19], v[8:9] op_sel_hi:[0,1]
	v_cvt_pk_bf16_f32 v87, v6, v7
	v_pk_mul_f32 v[6:7], v[18:19], v[10:11] op_sel_hi:[0,1]
	v_cvt_pk_bf16_f32 v100, v50, v0
	v_cvt_pk_bf16_f32 v101, v51, v1
	v_cvt_pk_bf16_f32 v102, v52, v2
	v_cvt_pk_bf16_f32 v103, v53, v3
	v_xor_b32_e32 v0, 0x80000000, v104
	v_xor_b32_e32 v1, 0x80000000, v105
	v_xor_b32_e32 v2, 0x80000000, v106
	v_xor_b32_e32 v3, 0x80000000, v107
	v_pk_fma_f32 v[4:5], v[22:23], v[12:13], v[4:5] op_sel_hi:[0,1,1]
	v_pk_fma_f32 v[6:7], v[22:23], v[14:15], v[6:7] op_sel_hi:[0,1,1]
	v_cvt_pk_bf16_f32 v104, v58, v0
	v_cvt_pk_bf16_f32 v105, v59, v1
	v_cvt_pk_bf16_f32 v106, v60, v2
	v_cvt_pk_bf16_f32 v107, v61, v3
	v_xor_b32_e32 v0, 0x80000000, v138
	v_xor_b32_e32 v1, 0x80000000, v139
	v_xor_b32_e32 v2, 0x80000000, v140
	v_xor_b32_e32 v3, 0x80000000, v141
	v_cvt_pk_bf16_f32 v139, v142, v144
	v_cndmask_b32_e64 v142, v19, v16, s[0:1]
	v_cvt_pk_bf16_f32 v66, v62, v63
	v_cvt_pk_bf16_f32 v94, v4, v5
	v_cvt_pk_bf16_f32 v95, v6, v7
	v_cvt_pk_bf16_f32 v108, v108, v0
	v_cvt_pk_bf16_f32 v109, v109, v1
	v_cvt_pk_bf16_f32 v110, v110, v2
	v_cvt_pk_bf16_f32 v111, v111, v3
	v_cvt_pk_bf16_f32 v138, v131, v133
	v_cvt_pk_bf16_f32 v140, v23, v143
	v_cvt_pk_bf16_f32 v141, v25, v21
	v_xor_b32_e32 v143, 0x80000000, v142
	v_mov_b32_e32 v133, v132
	v_lshl_add_u64 v[144:145], v[126:127], 0, s[8:9]
	s_waitcnt vmcnt(0)
	v_mov_b32_e32 v152, v32
	v_mov_b32_e32 v153, v33
	v_mov_b32_e32 v156, v48
	v_mov_b32_e32 v157, v49
.LBB0_892:
	s_waitcnt vmcnt(2)
	v_mfma_f32_32x32x16_bf16 v[0:15], v[88:91], v[80:83], 0
	v_lshlrev_b32_e32 v150, 16, v156
	v_and_b32_e32 v151, 0xffff0000, v156
	v_lshlrev_b32_e32 v154, 16, v157
	v_and_b32_e32 v155, 0xffff0000, v157
	v_lshlrev_b32_e32 v146, 16, v152
	v_and_b32_e32 v147, 0xffff0000, v152
	v_lshlrev_b32_e32 v148, 16, v153
	v_mfma_f32_32x32x16_bf16 v[48:63], v[88:91], v[92:95], 0
	v_and_b32_e32 v149, 0xffff0000, v153
	s_add_i32 s4, s6, 1
	s_cmp_lt_u32 s6, 31
	v_ashrrev_i32_e32 v131, 31, v130
	s_cselect_b32 s8, s4, s6
	s_lshl_b64 s[6:7], s[8:9], 17
	v_lshl_add_u32 v190, s8, 5, v136
	v_or_b32_e32 v192, 16, v190
	v_ashrrev_i32_e32 v191, 31, v190
	v_ashrrev_i32_e32 v193, 31, v192
	v_lshlrev_b64 v[190:191], 12, v[190:191]
	v_lshlrev_b64 v[192:193], 12, v[192:193]
	v_lshl_add_u64 v[190:191], v[144:145], 0, v[190:191]
	v_lshl_add_u64 v[192:193], v[144:145], 0, v[192:193]
	global_load_dwordx2 v[152:153], v[190:191], off offset:3072
	global_load_dwordx2 v[156:157], v[192:193], off offset:3072
	v_mfma_f32_32x32x16_bf16 v[16:31], v[88:91], v[64:67], 0
	s_nop 4
	v_permlane32_swap_b32_e32 v0, v48
	v_fmac_f32_e32 v0, v142, v129
	v_fmac_f32_e32 v0, v132, v128
	v_permlane32_swap_b32_e32 v1, v49
	v_permlane32_swap_b32_e32 v2, v50
	v_mfma_f32_32x32x16_bf16 v[32:47], v[88:91], v[84:87], 0
	v_permlane32_swap_b32_e32 v3, v51
	v_lshlrev_b64 v[88:89], 11, v[130:131]
	v_add_u32_e32 v137, s18, v122
	v_lshl_add_u64 v[170:171], s[88:89], 0, v[88:89]
	v_lshl_add_u64 v[88:89], v[134:135], 0, s[6:7]
	global_load_dwordx4 v[88:91], v[88:89], off offset:3072
	s_nop 5
	v_permlane32_swap_b32_e32 v16, v32
	v_permlane32_swap_b32_e32 v17, v33
	v_fma_f32 v16, -v142, v128, v16
	v_fmac_f32_e32 v16, v132, v129
	v_fma_f32 v17, -v142, v0, v17
	v_fmac_f32_e32 v1, v142, v16
	v_fmac_f32_e32 v17, v132, v16
	v_permlane32_swap_b32_e32 v18, v34
	v_fmac_f32_e32 v1, v132, v0
	v_fmac_f32_e32 v2, v142, v17
	v_permlane32_swap_b32_e32 v19, v35
	v_cvt_pk_bf16_f32 v128, v16, v0
	v_fma_f32 v16, -v142, v1, v18
	v_fmac_f32_e32 v2, v132, v1
	v_cvt_pk_bf16_f32 v0, v17, v1
	v_fmac_f32_e32 v16, v132, v17
	v_fma_f32 v1, -v142, v2, v19
	v_fmac_f32_e32 v3, v142, v16
	v_fmac_f32_e32 v1, v132, v16
	v_fmac_f32_e32 v3, v132, v2
	v_fmac_f32_e32 v48, v142, v1
	ds_write2_b32 v137, v128, v0 offset1:68
	v_cvt_pk_bf16_f32 v0, v16, v2
	v_fma_f32 v16, -v142, v3, v32
	v_fmac_f32_e32 v48, v132, v3
	v_cvt_pk_bf16_f32 v2, v1, v3
	v_fmac_f32_e32 v16, v132, v1
	v_fma_f32 v1, -v142, v48, v33
	v_fmac_f32_e32 v49, v142, v16
	v_fmac_f32_e32 v1, v132, v16
	v_fmac_f32_e32 v49, v132, v48
	v_fmac_f32_e32 v50, v142, v1
	v_fma_f32 v3, -v142, v49, v34
; #define LAS __attribute__((address_space(3)))
; __device__ __forceinline__ unsigned pk2(float lo, float hi) { f32x2 v; v.x = lo; v.y = hi; return __builtin_bit_cast(unsigned, __builtin_convertvector(v, hwbf2)); }
; template <bool STORE>
; __device__ __forceinline__ void s5_block(const Args& a, const S5Consts& c, const bf16x8 uf, int lane, float& hr, float& hi, LAS unsigned char* wl, const bf16_t* nxt, bf16x8& nuf) {
;     ...
; #pragma unroll
;     for (int ib = 0; ib < 4; ++ib) {
; #pragma unroll
;         for (int j = 0; j < 4; ++j) { const float nr = __builtin_fmaf(c.lbr, hr, __builtin_fmaf(nlbi, hi, bu[0][4 * ib + j])), ni = __builtin_fmaf(c.lbr, hi, __builtin_fmaf(c.lbi, hr, bu[1][4 * ib + j])); hr = nr; hi = ni; if (STORE) *(LAS unsigned*)(wl + (8 * ib + j) * 272 + lane * 4) = pk2(hr, hi); }
; #pragma unroll
;         for (int j = 0; j < 4; ++j) { const float nr = __builtin_fmaf(c.lbr, hr, __builtin_fmaf(nlbi, hi, bu[2][4 * ib + j])), ni = __builtin_fmaf(c.lbr, hi, __builtin_fmaf(c.lbi, hr, bu[3][4 * ib + j])); hr = nr; hi = ni; if (STORE) *(LAS unsigned*)(wl + (8 * ib + 4 + j) * 272 + lane * 4) = pk2(hr, hi); }
;     }
; __device__ __forceinline__ void s5_passC_run(const Args& a, LAS unsigned char* wlds, int row0, int nblk, int g, int lane, float& hr, float& hi) {
;     ...
;         for (int sb = 0; sb < 2; ++sb) uun[sb] = *(const u32x2*)(proj + (size_t)(row0 + nb * 32 + sb * 16 + r16) * NPROJ + 1536 + g * 16 + 4 * q4);
	v_fmac_f32_e32 v50, v132, v49
	ds_write2_b32 v137, v0, v2 offset0:136 offset1:204
	v_cvt_pk_bf16_f32 v2, v1, v49
	v_fmac_f32_e32 v3, v132, v1
	v_fma_f32 v1, -v142, v50, v35
	v_permlane32_swap_b32_e32 v4, v52
	v_fmac_f32_e32 v51, v142, v3
	v_fmac_f32_e32 v1, v132, v3
	v_add_u32_e32 v175, 0x400, v137
	v_permlane32_swap_b32_e32 v20, v36
	v_cvt_pk_bf16_f32 v0, v16, v48
	v_fmac_f32_e32 v51, v132, v50
	v_fmac_f32_e32 v4, v142, v1
	v_permlane32_swap_b32_e32 v21, v37
	ds_write2_b32 v175, v0, v2 offset0:16 offset1:84
	v_cvt_pk_bf16_f32 v0, v3, v50
	v_fma_f32 v3, -v142, v51, v20
	v_fmac_f32_e32 v4, v132, v51
	v_permlane32_swap_b32_e32 v5, v53
	v_cvt_pk_bf16_f32 v2, v1, v51
	v_fmac_f32_e32 v3, v132, v1
	v_fma_f32 v1, -v142, v4, v21
	v_permlane32_swap_b32_e32 v6, v54
	v_fmac_f32_e32 v5, v142, v3
	v_fmac_f32_e32 v1, v132, v3
	v_permlane32_swap_b32_e32 v22, v38
	v_fmac_f32_e32 v5, v132, v4
	v_fmac_f32_e32 v6, v142, v1
	v_permlane32_swap_b32_e32 v23, v39
	ds_write2_b32 v175, v0, v2 offset0:152 offset1:220
	v_cvt_pk_bf16_f32 v0, v3, v4
	v_fma_f32 v3, -v142, v5, v22
	v_fmac_f32_e32 v6, v132, v5
	v_permlane32_swap_b32_e32 v7, v55
	v_cvt_pk_bf16_f32 v2, v1, v5
	v_fmac_f32_e32 v3, v132, v1
	v_fma_f32 v1, -v142, v6, v23
	v_fmac_f32_e32 v7, v142, v3
	v_fmac_f32_e32 v1, v132, v3
	v_add_u32_e32 v178, 0x800, v137
	v_fmac_f32_e32 v7, v132, v6
	v_fmac_f32_e32 v52, v142, v1
	ds_write2_b32 v178, v0, v2 offset0:32 offset1:100
	v_cvt_pk_bf16_f32 v0, v3, v6
	v_fma_f32 v3, -v142, v7, v36
	v_fmac_f32_e32 v52, v132, v7
	v_cvt_pk_bf16_f32 v2, v1, v7
	v_fmac_f32_e32 v3, v132, v1
	v_fma_f32 v1, -v142, v52, v37
	v_fmac_f32_e32 v53, v142, v3
	v_fmac_f32_e32 v1, v132, v3
	v_fmac_f32_e32 v53, v132, v52
	v_fmac_f32_e32 v54, v142, v1
	ds_write2_b32 v178, v0, v2 offset0:168 offset1:236
	v_cvt_pk_bf16_f32 v0, v3, v52
	v_fma_f32 v3, -v142, v53, v38
	v_fmac_f32_e32 v54, v132, v53
	v_cvt_pk_bf16_f32 v2, v1, v53
	v_fmac_f32_e32 v3, v132, v1
	v_fma_f32 v1, -v142, v54, v39
	v_permlane32_swap_b32_e32 v8, v56
	v_fmac_f32_e32 v55, v142, v3
	v_fmac_f32_e32 v1, v132, v3
	v_add_u32_e32 v179, 0xc00, v137
	v_permlane32_swap_b32_e32 v24, v40
	v_fmac_f32_e32 v55, v132, v54
	v_fmac_f32_e32 v8, v142, v1
	v_permlane32_swap_b32_e32 v25, v41
	ds_write2_b32 v179, v0, v2 offset0:48 offset1:116
	v_cvt_pk_bf16_f32 v0, v3, v54
	v_fma_f32 v3, -v142, v55, v24
	v_fmac_f32_e32 v8, v132, v55
	v_permlane32_swap_b32_e32 v9, v57
	v_cvt_pk_bf16_f32 v2, v1, v55
	v_fmac_f32_e32 v3, v132, v1
	v_fma_f32 v1, -v142, v8, v25
	v_permlane32_swap_b32_e32 v10, v58
	v_fmac_f32_e32 v9, v142, v3
	v_fmac_f32_e32 v1, v132, v3
	v_permlane32_swap_b32_e32 v26, v42
	v_fmac_f32_e32 v9, v132, v8
	v_fmac_f32_e32 v10, v142, v1
	v_permlane32_swap_b32_e32 v27, v43
	ds_write2_b32 v179, v0, v2 offset0:184 offset1:252
	v_cvt_pk_bf16_f32 v0, v3, v8
	v_fma_f32 v3, -v142, v9, v26
	v_fmac_f32_e32 v10, v132, v9
	v_add_u32_e32 v188, 16, v130
	v_permlane32_swap_b32_e32 v11, v59
	v_cvt_pk_bf16_f32 v2, v1, v9
	v_fmac_f32_e32 v3, v132, v1
	v_fma_f32 v1, -v142, v10, v27
	v_ashrrev_i32_e32 v189, 31, v188
	v_fmac_f32_e32 v11, v142, v3
	v_fmac_f32_e32 v1, v132, v3
	v_add_u32_e32 v180, 0x1000, v137
	v_lshlrev_b64 v[172:173], 11, v[188:189]
	v_fmac_f32_e32 v11, v132, v10
	v_fmac_f32_e32 v56, v142, v1
	ds_write2_b32 v180, v0, v2 offset0:64 offset1:132
	v_cvt_pk_bf16_f32 v0, v3, v10
	v_fma_f32 v3, -v142, v11, v40
	v_fmac_f32_e32 v56, v132, v11
	v_cvt_pk_bf16_f32 v2, v1, v11
	v_fmac_f32_e32 v3, v132, v1
	v_fma_f32 v1, -v142, v56, v41
	v_fmac_f32_e32 v57, v142, v3
	v_fmac_f32_e32 v1, v132, v3
	v_add_u32_e32 v181, 0x1200, v137
	v_fmac_f32_e32 v57, v132, v56
	v_fmac_f32_e32 v58, v142, v1
	ds_write2_b32 v181, v0, v2 offset0:72 offset1:140
	v_cvt_pk_bf16_f32 v0, v3, v56
	v_fma_f32 v3, -v142, v57, v42
	v_fmac_f32_e32 v58, v132, v57
	v_cvt_pk_bf16_f32 v2, v1, v57
	v_fmac_f32_e32 v3, v132, v1
	v_fma_f32 v1, -v142, v58, v43
	v_permlane32_swap_b32_e32 v12, v60
	v_fmac_f32_e32 v59, v142, v3
	v_fmac_f32_e32 v1, v132, v3
	v_add_u32_e32 v182, 0x1400, v137
	v_permlane32_swap_b32_e32 v28, v44
	v_fmac_f32_e32 v59, v132, v58
	v_fmac_f32_e32 v12, v142, v1
	v_permlane32_swap_b32_e32 v29, v45
	ds_write2_b32 v182, v0, v2 offset0:80 offset1:148
	v_cvt_pk_bf16_f32 v0, v3, v58
	v_fma_f32 v3, -v142, v59, v28
	v_fmac_f32_e32 v12, v132, v59
	v_permlane32_swap_b32_e32 v13, v61
	v_cvt_pk_bf16_f32 v2, v1, v59
	v_fmac_f32_e32 v3, v132, v1
	v_fma_f32 v1, -v142, v12, v29
	v_permlane32_swap_b32_e32 v14, v62
	v_fmac_f32_e32 v13, v142, v3
	v_fmac_f32_e32 v1, v132, v3
	v_add_u32_e32 v183, 0x1600, v137
	v_permlane32_swap_b32_e32 v30, v46
	v_fmac_f32_e32 v13, v132, v12
	v_fmac_f32_e32 v14, v142, v1
	v_permlane32_swap_b32_e32 v31, v47
	ds_write2_b32 v183, v0, v2 offset0:88 offset1:156
	v_cvt_pk_bf16_f32 v0, v3, v12
	v_fma_f32 v3, -v142, v13, v30
	v_fmac_f32_e32 v14, v132, v13
	v_permlane32_swap_b32_e32 v15, v63
	v_cvt_pk_bf16_f32 v2, v1, v13
	v_fmac_f32_e32 v3, v132, v1
	v_fma_f32 v1, -v142, v14, v31
	v_fmac_f32_e32 v15, v142, v3
	v_fmac_f32_e32 v1, v132, v3
	v_add_u32_e32 v184, 0x1800, v137
	v_fmac_f32_e32 v15, v132, v14
	v_fmac_f32_e32 v60, v142, v1
	v_add_u32_e32 v185, 0x1a00, v137
	ds_write2_b32 v184, v0, v2 offset0:96 offset1:164
	v_cvt_pk_bf16_f32 v0, v3, v14
	v_cvt_pk_bf16_f32 v2, v1, v15
	v_fma_f32 v3, -v142, v15, v44
	v_fmac_f32_e32 v60, v132, v15
	ds_write2_b32 v185, v0, v2 offset0:104 offset1:172
	v_fmac_f32_e32 v3, v132, v1
	v_fma_f32 v2, -v142, v60, v45
	v_fmac_f32_e32 v61, v142, v3
	v_fmac_f32_e32 v2, v132, v3
	v_fmac_f32_e32 v61, v132, v60
	v_fmac_f32_e32 v62, v142, v2
	v_add_u32_e32 v186, 0x1c00, v137
	v_cvt_pk_bf16_f32 v1, v3, v60
	v_cvt_pk_bf16_f32 v3, v2, v61
	v_fma_f32 v0, -v142, v61, v46
	v_fmac_f32_e32 v62, v132, v61
	v_mov_b32_e32 v46, v63
	ds_write2_b32 v186, v1, v3 offset0:112 offset1:180
	v_fmac_f32_e32 v0, v132, v2
	v_mov_b32_e32 v1, v62
	v_cvt_pk_bf16_f32 v2, v0, v62
	v_mov_b32_e32 v63, v0
	v_pk_fma_f32 v[0:1], v[142:143], v[0:1], v[46:47]
	v_add_u32_e32 v187, 0x1e00, v137
	v_pk_fma_f32 v[128:129], v[132:133], v[62:63], v[0:1]
	v_add_u32_e32 v174, v159, v160
	v_cvt_pk_bf16_f32 v0, v129, v128
	ds_write2_b32 v187, v2, v0 offset0:120 offset1:188
	s_waitcnt lgkmcnt(0)
; #define LAS __attribute__((address_space(3)))
; __device__ __forceinline__ float bf2f(unsigned v) { return __uint_as_float(v << 16); }
; __device__ __forceinline__ unsigned pk2(float lo, float hi) { f32x2 v; v.x = lo; v.y = hi; return __builtin_bit_cast(unsigned, __builtin_convertvector(v, hwbf2)); }
; __device__ __forceinline__ void s5_passC_run(const Args& a, LAS unsigned char* wlds, int row0, int nblk, int g, int lane, float& hr, float& hi) {
;     ...
;         for (int sb = 0; sb < 2; ++sb) {
;             f32x4 y = (f32x4){0.f, 0.f, 0.f, 0.f};
; #pragma unroll
;             for (int kb = 0; kb < 4; ++kb) { const bf16x8 hb = *(const LAS bf16x8*)(wlds + (sb * 16 + r16) * S5_LD + (32 * kb + 8 * q4) * 2);
;                 y = __builtin_amdgcn_mfma_f32_16x16x32_bf16(ca[kb], hb, y, 0, 0, 0); }
;             const int row = rb + sb * 16 + r16;
;             const u32x2 uu = uus[sb];
;             const float uv[4] = {bf2f(uu.x & 0xffff), bf2f(uu.x >> 16), bf2f(uu.y & 0xffff), bf2f(uu.y >> 16)};
;             float ge[4];
; #pragma unroll
;             for (int j = 0; j < 4; ++j) ge[j] = gelu_tanh(y[j] + dD[j] * uv[j]);
;             u32x2 gw; gw.x = pk2(ge[0], ge[1]); gw.y = pk2(ge[2], ge[3]);
;             const bf16x4 gbf = __builtin_bit_cast(bf16x4, gw);
;             const f32x4 o0 = __builtin_amdgcn_mfma_f32_16x16x16bf16_1k(ga[0], gbf, gb0, 0, 0, 0);
;             const f32x4 o1 = __builtin_amdgcn_mfma_f32_16x16x16bf16_1k(ga[1], gbf, gb1, 0, 0, 0);
;             float ov[4];
; #pragma unroll
;             for (int j = 0; j < 4; ++j) ov[j] = o0[j] * __builtin_amdgcn_rcpf(1.f + __builtin_amdgcn_exp2f(-1.4426950409f * o1[j]));
;             u32x2 ow; ow.x = pk2(ov[0], ov[1]); ow.y = pk2(ov[2], ov[3]);
;             *(u32x2*)(mixin + (size_t)row * DM + 512 + g * 16 + 4 * q4) = ow;
;         }
;         asm volatile("s_waitcnt lgkmcnt(0)" ::: "memory");
;         uus[0] = uun[0]; uus[1] = uun[1];
	ds_read_b128 v[0:3], v174
	ds_read_b128 v[4:7], v174 offset:64
	ds_read_b128 v[8:11], v174 offset:4352
	ds_read_b128 v[12:15], v174 offset:4416
	s_waitcnt lgkmcnt(3)
	v_mfma_f32_16x16x32_bf16 v[0:3], v[96:99], v[0:3], 0
	s_mov_b32 s3, s9
	v_lshl_add_u64 v[16:17], v[170:171], 0, s[2:3]
	v_lshl_add_u64 v[18:19], s[88:89], 0, v[172:173]
	s_waitcnt lgkmcnt(1)
	v_mfma_f32_16x16x32_bf16 v[8:11], v[96:99], v[8:11], 0
	v_lshl_add_u64 v[20:21], v[16:17], 0, v[112:113]
	v_lshl_add_u64 v[22:23], v[18:19], 0, s[2:3]
	v_add_co_u32_e32 v20, vcc, s55, v20
	v_mfma_f32_16x16x32_bf16 v[0:3], v[100:103], v[4:7], v[0:3]
	s_nop 0
	v_addc_co_u32_e32 v21, vcc, 0, v21, vcc
	v_add_u32_e32 v130, 32, v130
	s_waitcnt lgkmcnt(0)
	v_mfma_f32_16x16x32_bf16 v[4:7], v[100:103], v[12:15], v[8:11]
	s_nop 2
	ds_read_b128 v[8:11], v174 offset:128
	ds_read_b128 v[12:15], v174 offset:192
	s_mov_b32 s6, s4
	s_cmp_eq_u32 s4, 32
	s_waitcnt lgkmcnt(1)
	v_mfma_f32_16x16x32_bf16 v[0:3], v[104:107], v[8:11], v[0:3]
	ds_read_b128 v[8:11], v174 offset:4480
	ds_read_b128 v[16:19], v174 offset:4544
	s_waitcnt lgkmcnt(1)
	v_mfma_f32_16x16x32_bf16 v[4:7], v[104:107], v[8:11], v[4:7]
	v_mfma_f32_16x16x32_bf16 v[0:3], v[108:111], v[12:15], v[0:3]
	v_lshl_add_u64 v[12:13], v[22:23], 0, v[112:113]
	v_add_co_u32_e32 v22, vcc, 0x22c00000, v12
	s_waitcnt lgkmcnt(0)
	v_mfma_f32_16x16x32_bf16 v[4:7], v[108:111], v[16:19], v[4:7]
	v_addc_co_u32_e32 v23, vcc, 0, v13, vcc
	s_nop 2
	v_pk_fma_f32 v[0:1], v[68:69], v[146:147], v[0:1]
	v_pk_fma_f32 v[2:3], v[70:71], v[148:149], v[2:3]
	s_nop 0
	v_pk_mul_f32 v[10:11], v[2:3], v[2:3]
	v_pk_fma_f32 v[4:5], v[68:69], v[150:151], v[4:5]
	v_pk_fma_f32 v[8:9], v[70:71], v[154:155], v[6:7]
	v_pk_mul_f32 v[6:7], v[0:1], v[0:1]
	v_pk_mul_f32 v[14:15], v[4:5], v[4:5]
	v_pk_mul_f32 v[16:17], v[8:9], v[8:9]
	v_fmamk_f32 v6, v6, 0xbdd2d3e2, v163
	v_fmamk_f32 v7, v7, 0xbdd2d3e2, v163
	v_fmamk_f32 v10, v10, 0xbdd2d3e2, v163
	v_fmamk_f32 v11, v11, 0xbdd2d3e2, v163
	v_fmamk_f32 v12, v14, 0xbdd2d3e2, v163
	v_fmamk_f32 v14, v15, 0xbdd2d3e2, v163
	v_fmamk_f32 v15, v16, 0xbdd2d3e2, v163
	v_fmamk_f32 v16, v17, 0xbdd2d3e2, v163
	v_mul_f32_e32 v6, v0, v6
	v_mul_f32_e32 v7, v1, v7
	v_mul_f32_e32 v10, v2, v10
	v_mul_f32_e32 v11, v3, v11
	v_mul_f32_e32 v12, v4, v12
	v_mul_f32_e32 v14, v5, v14
	v_mul_f32_e32 v15, v8, v15
	v_mul_f32_e32 v16, v9, v16
	v_exp_f32_e32 v6, v6
	v_exp_f32_e32 v7, v7
	v_exp_f32_e32 v10, v10
	v_exp_f32_e32 v11, v11
	v_exp_f32_e32 v12, v12
	v_exp_f32_e32 v14, v14
	v_exp_f32_e32 v15, v15
	v_exp_f32_e32 v16, v16
	v_add_f32_e32 v6, 1.0, v6
	v_add_f32_e32 v7, 1.0, v7
	v_add_f32_e32 v10, 1.0, v10
	v_add_f32_e32 v11, 1.0, v11
	v_add_f32_e32 v12, 1.0, v12
	v_add_f32_e32 v17, 1.0, v14
	v_add_f32_e32 v18, 1.0, v15
	v_add_f32_e32 v19, 1.0, v16
	v_rcp_f32_e32 v6, v6
	v_rcp_f32_e32 v7, v7
	v_rcp_f32_e32 v10, v10
	v_rcp_f32_e32 v11, v11
	v_rcp_f32_e32 v14, v12
	v_rcp_f32_e32 v15, v17
	v_rcp_f32_e32 v16, v18
	v_rcp_f32_e32 v17, v19
	v_pk_mul_f32 v[0:1], v[0:1], v[6:7]
	v_pk_mul_f32 v[2:3], v[2:3], v[10:11]
	v_cvt_pk_bf16_f32 v6, v0, v1
	v_cvt_pk_bf16_f32 v7, v2, v3
	v_pk_mul_f32 v[10:11], v[4:5], v[14:15]
	v_pk_mul_f32 v[8:9], v[8:9], v[16:17]
	v_mfma_f32_16x16x16_bf16 v[0:3], v[138:139], v[6:7], v[72:75]
	v_cvt_pk_bf16_f32 v14, v10, v11
	v_cvt_pk_bf16_f32 v15, v8, v9
	v_mfma_f32_16x16x16_bf16 v[4:7], v[140:141], v[6:7], v[76:79]
	s_nop 0
	v_mfma_f32_16x16x16_bf16 v[8:11], v[138:139], v[14:15], v[72:75]
	v_mfma_f32_16x16x16_bf16 v[12:15], v[140:141], v[14:15], v[76:79]
	s_nop 4
	v_mul_f32_e32 v4, 0xbfb8aa3b, v4
	v_mul_f32_e32 v5, 0xbfb8aa3b, v5
	v_mul_f32_e32 v6, 0xbfb8aa3b, v6
	v_mul_f32_e32 v7, 0xbfb8aa3b, v7
	v_exp_f32_e32 v4, v4
	v_mul_f32_e32 v12, 0xbfb8aa3b, v12
	v_mul_f32_e32 v13, 0xbfb8aa3b, v13
	v_mul_f32_e32 v14, 0xbfb8aa3b, v14
	v_mul_f32_e32 v15, 0xbfb8aa3b, v15
	v_exp_f32_e32 v5, v5
	v_exp_f32_e32 v6, v6
	v_exp_f32_e32 v7, v7
	v_exp_f32_e32 v12, v12
	v_exp_f32_e32 v13, v13
	v_exp_f32_e32 v14, v14
	v_exp_f32_e32 v15, v15
	v_add_f32_e32 v4, 1.0, v4
	v_add_f32_e32 v5, 1.0, v5
	v_add_f32_e32 v6, 1.0, v6
	v_add_f32_e32 v7, 1.0, v7
	v_add_f32_e32 v12, 1.0, v12
	v_add_f32_e32 v13, 1.0, v13
	v_add_f32_e32 v14, 1.0, v14
	v_add_f32_e32 v15, 1.0, v15
	v_rcp_f32_e32 v4, v4
	v_rcp_f32_e32 v5, v5
	v_rcp_f32_e32 v6, v6
	v_rcp_f32_e32 v7, v7
	v_rcp_f32_e32 v12, v12
	v_rcp_f32_e32 v13, v13
	v_rcp_f32_e32 v14, v14
	v_rcp_f32_e32 v15, v15
	v_pk_mul_f32 v[0:1], v[0:1], v[4:5]
	v_pk_mul_f32 v[2:3], v[2:3], v[6:7]
	v_pk_mul_f32 v[4:5], v[8:9], v[12:13]
	v_pk_mul_f32 v[6:7], v[10:11], v[14:15]
	v_cvt_pk_bf16_f32 v0, v0, v1
	v_cvt_pk_bf16_f32 v1, v2, v3
	v_cvt_pk_bf16_f32 v2, v4, v5
	v_cvt_pk_bf16_f32 v3, v6, v7
	global_store_dwordx2 v[20:21], v[0:1], off offset:1024
	global_store_dwordx2 v[22:23], v[2:3], off offset:1024
	s_waitcnt lgkmcnt(0)
	s_cbranch_scc0 .LBB0_892
	s_waitcnt vmcnt(0)
	s_branch .LBB0_855
